# EpiResid row sum-of-squares reduction: ds_bpermute round trips (lane^16, lane^32) replaced by v_permlane16_swap / v_permlane32_swap (lever 7: cross-lane VALU instead of LDS round trips)
# baseline (speedup 1.0000x reference)
; DI float shx(float v, int mask) { return __int_as_float(__builtin_amdgcn_ds_bpermute((lane_now() ^ mask) << 2, __float_as_int(v))); }
; DI void st_bf16x4(bf16_t* p, f32x4 v) { u32x2 o; o.x = pk2e(v[0], v[1]); o.y = pk2e(v[2], v[3]); *(u32x2*)p = o; }
;     ...
;         for (int ai = 0; ai < 2; ++ai)
; #pragma unroll
;           for (int m = 0; m < 4; ++m) {
;             float v = rowss[ai][m];
;             v += shx(v, 16); v += shx(v, 32);
;             if (fq_e == 0) red[(ai * HALF + wr * 64 + m * 16 + fr_e) * 4 + wc] = v;
;           }
;   DI float operator()(int row, int colbase, int fq, f32x4 v0, f32x4 v1) const {
;     ...
;     const f32x4 a = *(const f32x4*)(src + o) + v0, b = *(const f32x4*)(src + o + 16) + v1;
;     *(f32x4*)(dst + o) = a; *(f32x4*)(dst + o + 16) = b;
;     if (xb) { st_bf16x4(xb + o, a); st_bf16x4(xb + o + 16, b); }
;     return ((a[0] * a[0] + a[1] * a[1]) + (a[2] * a[2] + a[3] * a[3])) + ((b[0] * b[0] + b[1] * b[1]) + (b[2] * b[2] + b[3] * b[3]));
.LBB0_79:
	v_mul_f32_e32 v3, v3, v3
	v_fmac_f32_e32 v3, v2, v2
	v_mul_f32_e32 v2, v5, v5
	v_fmac_f32_e32 v2, v4, v4
	v_add_f32_e32 v2, v3, v2
	v_mul_f32_e32 v3, v7, v7
	v_mul_f32_e32 v4, v9, v9
	v_fmac_f32_e32 v3, v6, v6
	v_fmac_f32_e32 v4, v8, v8
	v_add_f32_e32 v3, v3, v4
	v_add_f32_e32 v2, v2, v3
	v_mul_f32_e32 v3, v19, v19
	v_mul_f32_e32 v4, v21, v21
	v_fmac_f32_e32 v3, v18, v18
	v_fmac_f32_e32 v4, v20, v20
	v_add_f32_e32 v3, v3, v4
	v_mul_f32_e32 v4, v23, v23
	v_mul_f32_e32 v5, v25, v25
	v_fmac_f32_e32 v4, v22, v22
	v_fmac_f32_e32 v5, v24, v24
	v_add_f32_e32 v4, v4, v5
	v_add_f32_e32 v3, v3, v4
	v_add_f32_e32 v2, v2, v3
	v_mov_b32_e32 v3, v199
	s_movk_i32 s0, 0x80
	v_lshlrev_b32_e32 v3, 2, v3
	v_bitop3_b32 v3, v3, 64, v193 bitop3:0x6c
	v_mov_b32_e32 v3, v2
	s_nop 1
	v_permlane16_swap_b32_e32 v3, v2
	v_or_b32_e32 v5, s34, v141
	v_cmp_eq_u32_e32 vcc, 0, v142
	s_waitcnt lgkmcnt(0)
	v_add_f32_e32 v3, v2, v3
	v_mov_b32_e32 v2, v199
	s_nop 0
	v_lshlrev_b32_e32 v2, 2, v2
	v_bitop3_b32 v2, v2, s0, v193 bitop3:0x6c
	v_mov_b32_e32 v4, v3
	s_nop 1
	v_permlane32_swap_b32_e32 v4, v3
	v_lshl_add_u32 v2, v5, 4, s37
	s_and_saveexec_b64 s[0:1], vcc
	s_cbranch_execz .LBB0_81
	s_waitcnt lgkmcnt(0)
	v_add_f32_e32 v3, v3, v4
	ds_write_b32 v2, v3
.LBB0_81:
	s_or_b64 exec, exec, s[0:1]
	v_mul_f32_e32 v3, v31, v31
	s_waitcnt lgkmcnt(0)
	v_mul_f32_e32 v4, v33, v33
	v_fmac_f32_e32 v3, v30, v30
	v_fmac_f32_e32 v4, v32, v32
	v_add_f32_e32 v3, v3, v4
	v_mul_f32_e32 v4, v39, v39
	v_mul_f32_e32 v5, v41, v41
	v_fmac_f32_e32 v4, v38, v38
	v_fmac_f32_e32 v5, v40, v40
	v_add_f32_e32 v4, v4, v5
	v_add_f32_e32 v3, v3, v4
	v_mul_f32_e32 v4, v43, v43
	v_mul_f32_e32 v5, v45, v45
	v_fmac_f32_e32 v4, v42, v42
	v_fmac_f32_e32 v5, v44, v44
	v_add_f32_e32 v4, v4, v5
	v_mul_f32_e32 v5, v47, v47
	v_mul_f32_e32 v6, v49, v49
	v_fmac_f32_e32 v5, v46, v46
	v_fmac_f32_e32 v6, v48, v48
	v_add_f32_e32 v5, v5, v6
	v_add_f32_e32 v4, v4, v5
	v_add_f32_e32 v3, v3, v4
	v_mov_b32_e32 v4, v199
	s_movk_i32 s0, 0x80
	v_lshlrev_b32_e32 v4, 2, v4
	v_bitop3_b32 v4, v4, 64, v193 bitop3:0x6c
	v_mov_b32_e32 v4, v3
	s_nop 1
	v_permlane16_swap_b32_e32 v4, v3
	s_waitcnt lgkmcnt(0)
	v_add_f32_e32 v3, v3, v4
	v_mov_b32_e32 v4, v199
	s_nop 0
	v_lshlrev_b32_e32 v4, 2, v4
	v_bitop3_b32 v4, v4, s0, v193 bitop3:0x6c
	v_mov_b32_e32 v4, v3
	s_nop 1
	v_permlane32_swap_b32_e32 v4, v3
	s_and_saveexec_b64 s[0:1], vcc
	s_cbranch_execz .LBB0_83
	s_waitcnt lgkmcnt(0)
	v_add_f32_e32 v3, v3, v4
	ds_write_b32 v2, v3 offset:256
.LBB0_83:
	s_or_b64 exec, exec, s[0:1]
	v_mul_f32_e32 v3, v59, v59
	s_waitcnt lgkmcnt(0)
	v_mul_f32_e32 v4, v61, v61
	v_fmac_f32_e32 v3, v58, v58
	v_fmac_f32_e32 v4, v60, v60
	v_add_f32_e32 v3, v3, v4
	v_mul_f32_e32 v4, v63, v63
	v_mul_f32_e32 v5, v65, v65
	v_fmac_f32_e32 v4, v62, v62
	v_fmac_f32_e32 v5, v64, v64
	v_add_f32_e32 v4, v4, v5
	v_add_f32_e32 v3, v3, v4
	v_mul_f32_e32 v4, v75, v75
	v_mul_f32_e32 v5, v77, v77
	v_fmac_f32_e32 v4, v74, v74
	v_fmac_f32_e32 v5, v76, v76
	v_add_f32_e32 v4, v4, v5
	v_mul_f32_e32 v5, v79, v79
	v_mul_f32_e32 v6, v81, v81
	v_fmac_f32_e32 v5, v78, v78
	v_fmac_f32_e32 v6, v80, v80
	v_add_f32_e32 v5, v5, v6
	v_add_f32_e32 v4, v4, v5
	v_add_f32_e32 v3, v3, v4
	v_mov_b32_e32 v4, v199
	s_movk_i32 s0, 0x80
	v_lshlrev_b32_e32 v4, 2, v4
	v_bitop3_b32 v4, v4, 64, v193 bitop3:0x6c
	v_mov_b32_e32 v4, v3
	s_nop 1
	v_permlane16_swap_b32_e32 v4, v3
	s_waitcnt lgkmcnt(0)
	v_add_f32_e32 v3, v3, v4
	v_mov_b32_e32 v4, v199
	s_nop 0
	v_lshlrev_b32_e32 v4, 2, v4
	v_bitop3_b32 v4, v4, s0, v193 bitop3:0x6c
	v_mov_b32_e32 v4, v3
	s_nop 1
	v_permlane32_swap_b32_e32 v4, v3
	s_and_saveexec_b64 s[0:1], vcc
	s_cbranch_execz .LBB0_85
	s_waitcnt lgkmcnt(0)
	v_add_f32_e32 v3, v3, v4
	ds_write_b32 v2, v3 offset:512
.LBB0_85:
	s_or_b64 exec, exec, s[0:1]
	v_mul_f32_e32 v3, v83, v83
	s_waitcnt lgkmcnt(0)
	v_mul_f32_e32 v4, v85, v85
	v_fmac_f32_e32 v3, v82, v82
	v_fmac_f32_e32 v4, v84, v84
	v_add_f32_e32 v3, v3, v4
	v_mul_f32_e32 v4, v87, v87
	v_mul_f32_e32 v5, v89, v89
	v_fmac_f32_e32 v4, v86, v86
	v_fmac_f32_e32 v5, v88, v88
	v_add_f32_e32 v4, v4, v5
	v_add_f32_e32 v3, v3, v4
	v_mul_f32_e32 v4, v99, v99
	v_mul_f32_e32 v5, v101, v101
	v_fmac_f32_e32 v4, v98, v98
	v_fmac_f32_e32 v5, v100, v100
	v_add_f32_e32 v4, v4, v5
	v_mul_f32_e32 v5, v103, v103
	v_mul_f32_e32 v6, v105, v105
	v_fmac_f32_e32 v5, v102, v102
	v_fmac_f32_e32 v6, v104, v104
	v_add_f32_e32 v5, v5, v6
	v_add_f32_e32 v4, v4, v5
	v_add_f32_e32 v3, v3, v4
	v_mov_b32_e32 v4, v199
	s_movk_i32 s0, 0x80
	v_lshlrev_b32_e32 v4, 2, v4
	v_bitop3_b32 v4, v4, 64, v193 bitop3:0x6c
	v_mov_b32_e32 v4, v3
	s_nop 1
	v_permlane16_swap_b32_e32 v4, v3
	s_waitcnt lgkmcnt(0)
	v_add_f32_e32 v3, v3, v4
	v_mov_b32_e32 v4, v199
	s_nop 0
	v_lshlrev_b32_e32 v4, 2, v4
	v_bitop3_b32 v4, v4, s0, v193 bitop3:0x6c
	v_mov_b32_e32 v4, v3
	s_nop 1
	v_permlane32_swap_b32_e32 v4, v3
	s_and_saveexec_b64 s[0:1], vcc
	s_cbranch_execz .LBB0_87
	s_waitcnt lgkmcnt(0)
	v_add_f32_e32 v3, v3, v4
	ds_write_b32 v2, v3 offset:768
; DI float shx(float v, int mask) { return __int_as_float(__builtin_amdgcn_ds_bpermute((lane_now() ^ mask) << 2, __float_as_int(v))); }
; DI void st_bf16x4(bf16_t* p, f32x4 v) { u32x2 o; o.x = pk2e(v[0], v[1]); o.y = pk2e(v[2], v[3]); *(u32x2*)p = o; }
;     ...
;         for (int ai = 0; ai < 2; ++ai)
; #pragma unroll
;           for (int m = 0; m < 4; ++m) {
;             float v = rowss[ai][m];
;             v += shx(v, 16); v += shx(v, 32);
;             if (fq_e == 0) red[(ai * HALF + wr * 64 + m * 16 + fr_e) * 4 + wc] = v;
;           }
;   DI float operator()(int row, int colbase, int fq, f32x4 v0, f32x4 v1) const {
;     ...
;     const f32x4 a = *(const f32x4*)(src + o) + v0, b = *(const f32x4*)(src + o + 16) + v1;
;     *(f32x4*)(dst + o) = a; *(f32x4*)(dst + o + 16) = b;
;     if (xb) { st_bf16x4(xb + o, a); st_bf16x4(xb + o + 16, b); }
;     return ((a[0] * a[0] + a[1] * a[1]) + (a[2] * a[2] + a[3] * a[3])) + ((b[0] * b[0] + b[1] * b[1]) + (b[2] * b[2] + b[3] * b[3]));
.LBB0_87:
	s_or_b64 exec, exec, s[0:1]
	v_mul_f32_e32 v3, v115, v115
	s_waitcnt lgkmcnt(0)
	v_mul_f32_e32 v4, v117, v117
	v_fmac_f32_e32 v3, v114, v114
	v_fmac_f32_e32 v4, v116, v116
	v_add_f32_e32 v3, v3, v4
	v_mul_f32_e32 v4, v119, v119
	v_mul_f32_e32 v5, v121, v121
	v_fmac_f32_e32 v4, v118, v118
	v_fmac_f32_e32 v5, v120, v120
	v_add_f32_e32 v4, v4, v5
	v_add_f32_e32 v3, v3, v4
	v_mul_f32_e32 v4, v127, v127
	v_mul_f32_e32 v5, v129, v129
	v_fmac_f32_e32 v4, v126, v126
	v_fmac_f32_e32 v5, v128, v128
	v_add_f32_e32 v4, v4, v5
	v_mul_f32_e32 v5, v123, v123
	v_mul_f32_e32 v6, v125, v125
	v_fmac_f32_e32 v5, v122, v122
	v_fmac_f32_e32 v6, v124, v124
	v_add_f32_e32 v5, v5, v6
	v_add_f32_e32 v4, v4, v5
	v_add_f32_e32 v3, v3, v4
	v_mov_b32_e32 v4, v199
	s_movk_i32 s0, 0x80
	v_lshlrev_b32_e32 v4, 2, v4
	v_bitop3_b32 v4, v4, 64, v193 bitop3:0x6c
	v_mov_b32_e32 v4, v3
	s_nop 1
	v_permlane16_swap_b32_e32 v4, v3
	s_waitcnt lgkmcnt(0)
	v_add_f32_e32 v3, v3, v4
	v_mov_b32_e32 v4, v199
	s_nop 0
	v_lshlrev_b32_e32 v4, 2, v4
	v_bitop3_b32 v4, v4, s0, v193 bitop3:0x6c
	v_mov_b32_e32 v4, v3
	s_nop 1
	v_permlane32_swap_b32_e32 v4, v3
	s_and_saveexec_b64 s[0:1], vcc
	s_cbranch_execz .LBB0_89
	s_waitcnt lgkmcnt(0)
	v_add_f32_e32 v3, v3, v4
	ds_write_b32 v2, v3 offset:2048
.LBB0_89:
	s_or_b64 exec, exec, s[0:1]
	v_mul_f32_e32 v3, v111, v111
	s_waitcnt lgkmcnt(0)
	v_mul_f32_e32 v4, v113, v113
	v_fmac_f32_e32 v3, v110, v110
	v_fmac_f32_e32 v4, v112, v112
	v_add_f32_e32 v3, v3, v4
	v_mul_f32_e32 v4, v107, v107
	v_mul_f32_e32 v5, v109, v109
	v_fmac_f32_e32 v4, v106, v106
	v_fmac_f32_e32 v5, v108, v108
	v_add_f32_e32 v4, v4, v5
	v_add_f32_e32 v3, v3, v4
	v_mul_f32_e32 v4, v95, v95
	v_mul_f32_e32 v5, v97, v97
	v_fmac_f32_e32 v4, v94, v94
	v_fmac_f32_e32 v5, v96, v96
	v_add_f32_e32 v4, v4, v5
	v_mul_f32_e32 v5, v91, v91
	v_mul_f32_e32 v6, v93, v93
	v_fmac_f32_e32 v5, v90, v90
	v_fmac_f32_e32 v6, v92, v92
	v_add_f32_e32 v5, v5, v6
	v_add_f32_e32 v4, v4, v5
	v_add_f32_e32 v3, v3, v4
	v_mov_b32_e32 v4, v199
	s_movk_i32 s0, 0x80
	v_lshlrev_b32_e32 v4, 2, v4
	v_bitop3_b32 v4, v4, 64, v193 bitop3:0x6c
	v_mov_b32_e32 v4, v3
	s_nop 1
	v_permlane16_swap_b32_e32 v4, v3
	s_waitcnt lgkmcnt(0)
	v_add_f32_e32 v3, v3, v4
	v_mov_b32_e32 v4, v199
	s_nop 0
	v_lshlrev_b32_e32 v4, 2, v4
	v_bitop3_b32 v4, v4, s0, v193 bitop3:0x6c
	v_mov_b32_e32 v4, v3
	s_nop 1
	v_permlane32_swap_b32_e32 v4, v3
	s_and_saveexec_b64 s[0:1], vcc
	s_cbranch_execz .LBB0_91
	s_waitcnt lgkmcnt(0)
	v_add_f32_e32 v3, v3, v4
	ds_write_b32 v2, v3 offset:2304
.LBB0_91:
	s_or_b64 exec, exec, s[0:1]
	v_mul_f32_e32 v3, v71, v71
	s_waitcnt lgkmcnt(0)
	v_mul_f32_e32 v4, v73, v73
	v_fmac_f32_e32 v3, v70, v70
	v_fmac_f32_e32 v4, v72, v72
	v_add_f32_e32 v3, v3, v4
	v_mul_f32_e32 v4, v67, v67
	v_mul_f32_e32 v5, v69, v69
	v_fmac_f32_e32 v4, v66, v66
	v_fmac_f32_e32 v5, v68, v68
	v_add_f32_e32 v4, v4, v5
	v_add_f32_e32 v3, v3, v4
	v_mul_f32_e32 v4, v55, v55
	v_mul_f32_e32 v5, v57, v57
	v_fmac_f32_e32 v4, v54, v54
	v_fmac_f32_e32 v5, v56, v56
	v_add_f32_e32 v4, v4, v5
	v_mul_f32_e32 v5, v51, v51
	v_mul_f32_e32 v6, v53, v53
	v_fmac_f32_e32 v5, v50, v50
	v_fmac_f32_e32 v6, v52, v52
	v_add_f32_e32 v5, v5, v6
	v_add_f32_e32 v4, v4, v5
	v_add_f32_e32 v3, v3, v4
	v_mov_b32_e32 v4, v199
	s_movk_i32 s0, 0x80
	v_lshlrev_b32_e32 v4, 2, v4
	v_bitop3_b32 v4, v4, 64, v193 bitop3:0x6c
	v_mov_b32_e32 v4, v3
	s_nop 1
	v_permlane16_swap_b32_e32 v4, v3
	s_waitcnt lgkmcnt(0)
	v_add_f32_e32 v3, v3, v4
	v_mov_b32_e32 v4, v199
	s_nop 0
	v_lshlrev_b32_e32 v4, 2, v4
	v_bitop3_b32 v4, v4, s0, v193 bitop3:0x6c
	v_mov_b32_e32 v4, v3
	s_nop 1
	v_permlane32_swap_b32_e32 v4, v3
	s_and_saveexec_b64 s[0:1], vcc
	s_cbranch_execz .LBB0_93
	s_waitcnt lgkmcnt(0)
	v_add_f32_e32 v3, v3, v4
	ds_write_b32 v2, v3 offset:2560
.LBB0_93:
	s_or_b64 exec, exec, s[0:1]
	v_mul_f32_e32 v3, v35, v35
	s_waitcnt lgkmcnt(0)
	v_mul_f32_e32 v4, v37, v37
	v_fmac_f32_e32 v3, v34, v34
	v_fmac_f32_e32 v4, v36, v36
	v_add_f32_e32 v3, v3, v4
	v_mul_f32_e32 v4, v27, v27
	v_mul_f32_e32 v5, v29, v29
	v_fmac_f32_e32 v4, v26, v26
	v_fmac_f32_e32 v5, v28, v28
	v_add_f32_e32 v4, v4, v5
	v_add_f32_e32 v3, v3, v4
	v_mul_f32_e32 v4, v15, v15
	v_mul_f32_e32 v5, v17, v17
	v_fmac_f32_e32 v4, v14, v14
	v_fmac_f32_e32 v5, v16, v16
	v_add_f32_e32 v4, v4, v5
	v_mul_f32_e32 v5, v11, v11
	v_mul_f32_e32 v6, v13, v13
	v_fmac_f32_e32 v5, v10, v10
	v_fmac_f32_e32 v6, v12, v12
	v_add_f32_e32 v5, v5, v6
	v_add_f32_e32 v4, v4, v5
	v_add_f32_e32 v3, v3, v4
	v_mov_b32_e32 v4, v199
	s_movk_i32 s0, 0x80
	v_lshlrev_b32_e32 v4, 2, v4
	v_bitop3_b32 v4, v4, 64, v193 bitop3:0x6c
	v_mov_b32_e32 v4, v3
	s_nop 1
	v_permlane16_swap_b32_e32 v4, v3
	s_waitcnt lgkmcnt(0)
	v_add_f32_e32 v3, v3, v4
	v_mov_b32_e32 v4, v199
	s_nop 0
	v_lshlrev_b32_e32 v4, 2, v4
	v_bitop3_b32 v4, v4, s0, v193 bitop3:0x6c
	v_mov_b32_e32 v4, v3
	s_nop 1
	v_permlane32_swap_b32_e32 v4, v3
	s_and_saveexec_b64 s[0:1], vcc
	s_cbranch_execz .LBB0_95
	s_waitcnt lgkmcnt(0)
	v_add_f32_e32 v3, v3, v4
	ds_write_b32 v2, v3 offset:2816

; DI float shx(float v, int mask) { return __int_as_float(__builtin_amdgcn_ds_bpermute((lane_now() ^ mask) << 2, __float_as_int(v))); }
; DI void st_bf16x4(bf16_t* p, f32x4 v) { u32x2 o; o.x = pk2e(v[0], v[1]); o.y = pk2e(v[2], v[3]); *(u32x2*)p = o; }
;     ...
;         for (int ai = 0; ai < 2; ++ai)
; #pragma unroll
;           for (int m = 0; m < 4; ++m) {
;             float v = rowss[ai][m];
;             v += shx(v, 16); v += shx(v, 32);
;             if (fq_e == 0) red[(ai * HALF + wr * 64 + m * 16 + fr_e) * 4 + wc] = v;
;           }
;   DI float operator()(int row, int colbase, int fq, f32x4 v0, f32x4 v1) const {
;     ...
;     const f32x4 a = *(const f32x4*)(src + o) + v0, b = *(const f32x4*)(src + o + 16) + v1;
;     *(f32x4*)(dst + o) = a; *(f32x4*)(dst + o + 16) = b;
;     if (xb) { st_bf16x4(xb + o, a); st_bf16x4(xb + o + 16, b); }
;     return ((a[0] * a[0] + a[1] * a[1]) + (a[2] * a[2] + a[3] * a[3])) + ((b[0] * b[0] + b[1] * b[1]) + (b[2] * b[2] + b[3] * b[3]));
.LBB0_171:
	v_mul_f32_e32 v3, v3, v3
	v_fmac_f32_e32 v3, v2, v2
	v_mul_f32_e32 v2, v5, v5
	v_fmac_f32_e32 v2, v4, v4
	v_add_f32_e32 v2, v3, v2
	v_mul_f32_e32 v3, v7, v7
	v_mul_f32_e32 v4, v9, v9
	v_fmac_f32_e32 v3, v6, v6
	v_fmac_f32_e32 v4, v8, v8
	v_add_f32_e32 v3, v3, v4
	v_add_f32_e32 v2, v2, v3
	v_mul_f32_e32 v3, v19, v19
	v_mul_f32_e32 v4, v21, v21
	v_fmac_f32_e32 v3, v18, v18
	v_fmac_f32_e32 v4, v20, v20
	v_add_f32_e32 v3, v3, v4
	v_mul_f32_e32 v4, v23, v23
	v_mul_f32_e32 v5, v25, v25
	v_fmac_f32_e32 v4, v22, v22
	v_fmac_f32_e32 v5, v24, v24
	v_add_f32_e32 v4, v4, v5
	v_add_f32_e32 v3, v3, v4
	v_add_f32_e32 v2, v2, v3
	v_mov_b32_e32 v3, v199
	s_movk_i32 s0, 0x80
	v_lshlrev_b32_e32 v3, 2, v3
	v_bitop3_b32 v3, v3, 64, v193 bitop3:0x6c
	v_mov_b32_e32 v3, v2
	s_nop 1
	v_permlane16_swap_b32_e32 v3, v2
	v_or_b32_e32 v5, s36, v143
	v_cmp_eq_u32_e32 vcc, 0, v144
	s_waitcnt lgkmcnt(0)
	v_add_f32_e32 v3, v2, v3
	v_mov_b32_e32 v2, v199
	s_nop 0
	v_lshlrev_b32_e32 v2, 2, v2
	v_bitop3_b32 v2, v2, s0, v193 bitop3:0x6c
	v_mov_b32_e32 v4, v3
	s_nop 1
	v_permlane32_swap_b32_e32 v4, v3
	v_lshl_add_u32 v2, v5, 4, s39
	s_and_saveexec_b64 s[0:1], vcc
	s_cbranch_execz .LBB0_173
	s_waitcnt lgkmcnt(0)
	v_add_f32_e32 v3, v3, v4
	ds_write_b32 v2, v3
.LBB0_173:
	s_or_b64 exec, exec, s[0:1]
	v_mul_f32_e32 v3, v35, v35
	s_waitcnt lgkmcnt(0)
	v_mul_f32_e32 v4, v37, v37
	v_fmac_f32_e32 v3, v34, v34
	v_fmac_f32_e32 v4, v36, v36
	v_add_f32_e32 v3, v3, v4
	v_mul_f32_e32 v4, v39, v39
	v_mul_f32_e32 v5, v41, v41
	v_fmac_f32_e32 v4, v38, v38
	v_fmac_f32_e32 v5, v40, v40
	v_add_f32_e32 v4, v4, v5
	v_add_f32_e32 v3, v3, v4
	v_mul_f32_e32 v4, v43, v43
	v_mul_f32_e32 v5, v45, v45
	v_fmac_f32_e32 v4, v42, v42
	v_fmac_f32_e32 v5, v44, v44
	v_add_f32_e32 v4, v4, v5
	v_mul_f32_e32 v5, v47, v47
	v_mul_f32_e32 v6, v49, v49
	v_fmac_f32_e32 v5, v46, v46
	v_fmac_f32_e32 v6, v48, v48
	v_add_f32_e32 v5, v5, v6
	v_add_f32_e32 v4, v4, v5
	v_add_f32_e32 v3, v3, v4
	v_mov_b32_e32 v4, v199
	s_movk_i32 s0, 0x80
	v_lshlrev_b32_e32 v4, 2, v4
	v_bitop3_b32 v4, v4, 64, v193 bitop3:0x6c
	v_mov_b32_e32 v4, v3
	s_nop 1
	v_permlane16_swap_b32_e32 v4, v3
	s_waitcnt lgkmcnt(0)
	v_add_f32_e32 v3, v3, v4
	v_mov_b32_e32 v4, v199
	s_nop 0
	v_lshlrev_b32_e32 v4, 2, v4
	v_bitop3_b32 v4, v4, s0, v193 bitop3:0x6c
	v_mov_b32_e32 v4, v3
	s_nop 1
	v_permlane32_swap_b32_e32 v4, v3
	s_and_saveexec_b64 s[0:1], vcc
	s_cbranch_execz .LBB0_175
	s_waitcnt lgkmcnt(0)
	v_add_f32_e32 v3, v3, v4
	ds_write_b32 v2, v3 offset:256

; DI float shx(float v, int mask) { return __int_as_float(__builtin_amdgcn_ds_bpermute((lane_now() ^ mask) << 2, __float_as_int(v))); }
; DI void st_bf16x4(bf16_t* p, f32x4 v) { u32x2 o; o.x = pk2e(v[0], v[1]); o.y = pk2e(v[2], v[3]); *(u32x2*)p = o; }
;     ...
;         for (int ai = 0; ai < 2; ++ai)
; #pragma unroll
;           for (int m = 0; m < 4; ++m) {
;             float v = rowss[ai][m];
;             v += shx(v, 16); v += shx(v, 32);
;             if (fq_e == 0) red[(ai * HALF + wr * 64 + m * 16 + fr_e) * 4 + wc] = v;
;           }
;   DI float operator()(int row, int colbase, int fq, f32x4 v0, f32x4 v1) const {
;     ...
;     const f32x4 a = *(const f32x4*)(src + o) + v0, b = *(const f32x4*)(src + o + 16) + v1;
;     *(f32x4*)(dst + o) = a; *(f32x4*)(dst + o + 16) = b;
;     if (xb) { st_bf16x4(xb + o, a); st_bf16x4(xb + o + 16, b); }
;     return ((a[0] * a[0] + a[1] * a[1]) + (a[2] * a[2] + a[3] * a[3])) + ((b[0] * b[0] + b[1] * b[1]) + (b[2] * b[2] + b[3] * b[3]));
.LBB0_177:
	s_or_b64 exec, exec, s[0:1]
	v_mul_f32_e32 v3, v87, v87
	s_waitcnt lgkmcnt(0)
	v_mul_f32_e32 v4, v89, v89
	v_fmac_f32_e32 v3, v86, v86
	v_fmac_f32_e32 v4, v88, v88
	v_add_f32_e32 v3, v3, v4
	v_mul_f32_e32 v4, v95, v95
	v_mul_f32_e32 v5, v97, v97
	v_fmac_f32_e32 v4, v94, v94
	v_fmac_f32_e32 v5, v96, v96
	v_add_f32_e32 v4, v4, v5
	v_add_f32_e32 v3, v3, v4
	v_mul_f32_e32 v4, v103, v103
	v_mul_f32_e32 v5, v105, v105
	v_fmac_f32_e32 v4, v102, v102
	v_fmac_f32_e32 v5, v104, v104
	v_add_f32_e32 v4, v4, v5
	v_mul_f32_e32 v5, v111, v111
	v_mul_f32_e32 v6, v113, v113
	v_fmac_f32_e32 v5, v110, v110
	v_fmac_f32_e32 v6, v112, v112
	v_add_f32_e32 v5, v5, v6
	v_add_f32_e32 v4, v4, v5
	v_add_f32_e32 v3, v3, v4
	v_mov_b32_e32 v4, v199
	s_movk_i32 s0, 0x80
	v_lshlrev_b32_e32 v4, 2, v4
	v_bitop3_b32 v4, v4, 64, v193 bitop3:0x6c
	v_mov_b32_e32 v4, v3
	s_nop 1
	v_permlane16_swap_b32_e32 v4, v3
	s_waitcnt lgkmcnt(0)
	v_add_f32_e32 v3, v3, v4
	v_mov_b32_e32 v4, v199
	s_nop 0
	v_lshlrev_b32_e32 v4, 2, v4
	v_bitop3_b32 v4, v4, s0, v193 bitop3:0x6c
	v_mov_b32_e32 v4, v3
	s_nop 1
	v_permlane32_swap_b32_e32 v4, v3
	s_and_saveexec_b64 s[0:1], vcc
	s_cbranch_execz .LBB0_179
	s_waitcnt lgkmcnt(0)
	v_add_f32_e32 v3, v3, v4
	ds_write_b32 v2, v3 offset:768

; DI float shx(float v, int mask) { return __int_as_float(__builtin_amdgcn_ds_bpermute((lane_now() ^ mask) << 2, __float_as_int(v))); }
; DI void st_bf16x4(bf16_t* p, f32x4 v) { u32x2 o; o.x = pk2e(v[0], v[1]); o.y = pk2e(v[2], v[3]); *(u32x2*)p = o; }
;     ...
;         for (int ai = 0; ai < 2; ++ai)
; #pragma unroll
;           for (int m = 0; m < 4; ++m) {
;             float v = rowss[ai][m];
;             v += shx(v, 16); v += shx(v, 32);
;             if (fq_e == 0) red[(ai * HALF + wr * 64 + m * 16 + fr_e) * 4 + wc] = v;
;           }
;   DI float operator()(int row, int colbase, int fq, f32x4 v0, f32x4 v1) const {
;     ...
;     const f32x4 a = *(const f32x4*)(src + o) + v0, b = *(const f32x4*)(src + o + 16) + v1;
;     *(f32x4*)(dst + o) = a; *(f32x4*)(dst + o + 16) = b;
;     if (xb) { st_bf16x4(xb + o, a); st_bf16x4(xb + o + 16, b); }
;     return ((a[0] * a[0] + a[1] * a[1]) + (a[2] * a[2] + a[3] * a[3])) + ((b[0] * b[0] + b[1] * b[1]) + (b[2] * b[2] + b[3] * b[3]));
.LBB0_181:
	s_or_b64 exec, exec, s[0:1]
	v_mul_f32_e32 v3, v107, v107
	s_waitcnt lgkmcnt(0)
	v_mul_f32_e32 v4, v109, v109
	v_fmac_f32_e32 v3, v106, v106
	v_fmac_f32_e32 v4, v108, v108
	v_add_f32_e32 v3, v3, v4
	v_mul_f32_e32 v4, v99, v99
	v_mul_f32_e32 v5, v101, v101
	v_fmac_f32_e32 v4, v98, v98
	v_fmac_f32_e32 v5, v100, v100
	v_add_f32_e32 v4, v4, v5
	v_add_f32_e32 v3, v3, v4
	v_mul_f32_e32 v4, v91, v91
	v_mul_f32_e32 v5, v93, v93
	v_fmac_f32_e32 v4, v90, v90
	v_fmac_f32_e32 v5, v92, v92
	v_add_f32_e32 v4, v4, v5
	v_mul_f32_e32 v5, v83, v83
	v_mul_f32_e32 v6, v85, v85
	v_fmac_f32_e32 v5, v82, v82
	v_fmac_f32_e32 v6, v84, v84
	v_add_f32_e32 v5, v5, v6
	v_add_f32_e32 v4, v4, v5
	v_add_f32_e32 v3, v3, v4
	v_mov_b32_e32 v4, v199
	s_movk_i32 s0, 0x80
	v_lshlrev_b32_e32 v4, 2, v4
	v_bitop3_b32 v4, v4, 64, v193 bitop3:0x6c
	v_mov_b32_e32 v4, v3
	s_nop 1
	v_permlane16_swap_b32_e32 v4, v3
	s_waitcnt lgkmcnt(0)
	v_add_f32_e32 v3, v3, v4
	v_mov_b32_e32 v4, v199
	s_nop 0
	v_lshlrev_b32_e32 v4, 2, v4
	v_bitop3_b32 v4, v4, s0, v193 bitop3:0x6c
	v_mov_b32_e32 v4, v3
	s_nop 1
	v_permlane32_swap_b32_e32 v4, v3
	s_and_saveexec_b64 s[0:1], vcc
	s_cbranch_execz .LBB0_183
	s_waitcnt lgkmcnt(0)
	v_add_f32_e32 v3, v3, v4
	ds_write_b32 v2, v3 offset:2304

; DI float shx(float v, int mask) { return __int_as_float(__builtin_amdgcn_ds_bpermute((lane_now() ^ mask) << 2, __float_as_int(v))); }
; DI void st_bf16x4(bf16_t* p, f32x4 v) { u32x2 o; o.x = pk2e(v[0], v[1]); o.y = pk2e(v[2], v[3]); *(u32x2*)p = o; }
;     ...
;         for (int ai = 0; ai < 2; ++ai)
; #pragma unroll
;           for (int m = 0; m < 4; ++m) {
;             float v = rowss[ai][m];
;             v += shx(v, 16); v += shx(v, 32);
;             if (fq_e == 0) red[(ai * HALF + wr * 64 + m * 16 + fr_e) * 4 + wc] = v;
;           }
;   DI float operator()(int row, int colbase, int fq, f32x4 v0, f32x4 v1) const {
;     ...
;     const f32x4 a = *(const f32x4*)(src + o) + v0, b = *(const f32x4*)(src + o + 16) + v1;
;     *(f32x4*)(dst + o) = a; *(f32x4*)(dst + o + 16) = b;
;     if (xb) { st_bf16x4(xb + o, a); st_bf16x4(xb + o + 16, b); }
;     return ((a[0] * a[0] + a[1] * a[1]) + (a[2] * a[2] + a[3] * a[3])) + ((b[0] * b[0] + b[1] * b[1]) + (b[2] * b[2] + b[3] * b[3]));
.LBB0_185:
	s_or_b64 exec, exec, s[0:1]
	v_mul_f32_e32 v3, v31, v31
	s_waitcnt lgkmcnt(0)
	v_mul_f32_e32 v4, v33, v33
	v_fmac_f32_e32 v3, v30, v30
	v_fmac_f32_e32 v4, v32, v32
	v_add_f32_e32 v3, v3, v4
	v_mul_f32_e32 v4, v27, v27
	v_mul_f32_e32 v5, v29, v29
	v_fmac_f32_e32 v4, v26, v26
	v_fmac_f32_e32 v5, v28, v28
	v_add_f32_e32 v4, v4, v5
	v_add_f32_e32 v3, v3, v4
	v_mul_f32_e32 v4, v15, v15
	v_mul_f32_e32 v5, v17, v17
	v_fmac_f32_e32 v4, v14, v14
	v_fmac_f32_e32 v5, v16, v16
	v_add_f32_e32 v4, v4, v5
	v_mul_f32_e32 v5, v11, v11
	v_mul_f32_e32 v6, v13, v13
	v_fmac_f32_e32 v5, v10, v10
	v_fmac_f32_e32 v6, v12, v12
	v_add_f32_e32 v5, v5, v6
	v_add_f32_e32 v4, v4, v5
	v_add_f32_e32 v3, v3, v4
	v_mov_b32_e32 v4, v199
	s_movk_i32 s0, 0x80
	v_lshlrev_b32_e32 v4, 2, v4
	v_bitop3_b32 v4, v4, 64, v193 bitop3:0x6c
	v_mov_b32_e32 v4, v3
	s_nop 1
	v_permlane16_swap_b32_e32 v4, v3
	s_waitcnt lgkmcnt(0)
	v_add_f32_e32 v3, v3, v4
	v_mov_b32_e32 v4, v199
	s_nop 0
	v_lshlrev_b32_e32 v4, 2, v4
	v_bitop3_b32 v4, v4, s0, v193 bitop3:0x6c
	v_mov_b32_e32 v4, v3
	s_nop 1
	v_permlane32_swap_b32_e32 v4, v3
	s_and_saveexec_b64 s[0:1], vcc
	s_cbranch_execz .LBB0_187
	s_waitcnt lgkmcnt(0)
	v_add_f32_e32 v3, v3, v4
	ds_write_b32 v2, v3 offset:2816

; DI float shx(float v, int mask) { return __int_as_float(__builtin_amdgcn_ds_bpermute((lane_now() ^ mask) << 2, __float_as_int(v))); }
; #define LAS __attribute__((address_space(3)))
; DI void st_bf16x4(bf16_t* p, f32x4 v) { u32x2 o; o.x = pk2e(v[0], v[1]); o.y = pk2e(v[2], v[3]); *(u32x2*)p = o; }
;     ...
;       if (ssp) {
;         LAS float* red = (LAS float*)lds;
; #pragma unroll
;         for (int ai = 0; ai < 2; ++ai)
; #pragma unroll
;           for (int m = 0; m < 4; ++m) {
;             float v = rowss[ai][m];
;             v += shx(v, 16); v += shx(v, 32);
;             if (fq_e == 0) red[(ai * HALF + wr * 64 + m * 16 + fr_e) * 4 + wc] = v;
;           }
;   DI float operator()(int row, int colbase, int fq, f32x4 v0, f32x4 v1) const {
;     ...
;     const f32x4 a = *(const f32x4*)(src + o) + v0, b = *(const f32x4*)(src + o + 16) + v1;
;     *(f32x4*)(dst + o) = a; *(f32x4*)(dst + o + 16) = b;
;     if (xb) { st_bf16x4(xb + o, a); st_bf16x4(xb + o + 16, b); }
;     return ((a[0] * a[0] + a[1] * a[1]) + (a[2] * a[2] + a[3] * a[3])) + ((b[0] * b[0] + b[1] * b[1]) + (b[2] * b[2] + b[3] * b[3]));
.LBB0_421:
	s_and_b64 vcc, exec, s[2:3]
	s_cbranch_vccz .LBB0_378
	v_mul_f32_e32 v3, v3, v3
	v_fmac_f32_e32 v3, v2, v2
	v_mul_f32_e32 v2, v5, v5
	v_fmac_f32_e32 v2, v4, v4
	v_add_f32_e32 v2, v3, v2
	v_mul_f32_e32 v3, v7, v7
	v_mul_f32_e32 v4, v9, v9
	v_fmac_f32_e32 v3, v6, v6
	v_fmac_f32_e32 v4, v8, v8
	v_add_f32_e32 v3, v3, v4
	v_add_f32_e32 v2, v2, v3
	v_mul_f32_e32 v3, v19, v19
	v_mul_f32_e32 v4, v21, v21
	v_fmac_f32_e32 v3, v18, v18
	v_fmac_f32_e32 v4, v20, v20
	v_add_f32_e32 v3, v3, v4
	v_mul_f32_e32 v4, v23, v23
	v_mul_f32_e32 v5, v25, v25
	v_fmac_f32_e32 v4, v22, v22
	v_fmac_f32_e32 v5, v24, v24
	v_add_f32_e32 v4, v4, v5
	v_add_f32_e32 v3, v3, v4
	v_add_f32_e32 v2, v2, v3
	v_mov_b32_e32 v3, v199
	s_movk_i32 s0, 0x80
	v_lshlrev_b32_e32 v3, 2, v3
	v_bitop3_b32 v3, v3, 64, v193 bitop3:0x6c
	v_mov_b32_e32 v3, v2
	s_nop 1
	v_permlane16_swap_b32_e32 v3, v2
	v_cmp_eq_u32_e32 vcc, 0, v144
	s_waitcnt lgkmcnt(0)
	v_add_f32_e32 v3, v2, v3
	v_mov_b32_e32 v2, v199
	s_nop 0
	v_lshlrev_b32_e32 v2, 2, v2
	v_bitop3_b32 v2, v2, s0, v193 bitop3:0x6c
	v_mov_b32_e32 v4, v3
	s_nop 1
	v_permlane32_swap_b32_e32 v4, v3
	v_or_b32_e32 v2, s28, v143
	v_lshl_add_u32 v2, v2, 4, s31
	s_and_saveexec_b64 s[0:1], vcc
	s_cbranch_execz .LBB0_424
	s_waitcnt lgkmcnt(0)
	v_add_f32_e32 v3, v3, v4
	ds_write_b32 v2, v3
.LBB0_424:
	s_or_b64 exec, exec, s[0:1]
	v_mul_f32_e32 v3, v35, v35
	s_waitcnt lgkmcnt(0)
	v_mul_f32_e32 v4, v37, v37
	v_fmac_f32_e32 v3, v34, v34
	v_fmac_f32_e32 v4, v36, v36
	v_add_f32_e32 v3, v3, v4
	v_mul_f32_e32 v4, v39, v39
	v_mul_f32_e32 v5, v41, v41
	v_fmac_f32_e32 v4, v38, v38
	v_fmac_f32_e32 v5, v40, v40
	v_add_f32_e32 v4, v4, v5
	v_add_f32_e32 v3, v3, v4
	v_mul_f32_e32 v4, v47, v47
	v_mul_f32_e32 v5, v49, v49
	v_fmac_f32_e32 v4, v46, v46
	v_fmac_f32_e32 v5, v48, v48
	v_add_f32_e32 v4, v4, v5
	v_mul_f32_e32 v5, v51, v51
	v_mul_f32_e32 v6, v53, v53
	v_fmac_f32_e32 v5, v50, v50
	v_fmac_f32_e32 v6, v52, v52
	v_add_f32_e32 v5, v5, v6
	v_add_f32_e32 v4, v4, v5
	v_add_f32_e32 v3, v3, v4
	v_mov_b32_e32 v4, v199
	s_movk_i32 s0, 0x80
	v_lshlrev_b32_e32 v4, 2, v4
	v_bitop3_b32 v4, v4, 64, v193 bitop3:0x6c
	v_mov_b32_e32 v4, v3
	s_nop 1
	v_permlane16_swap_b32_e32 v4, v3
	s_waitcnt lgkmcnt(0)
	v_add_f32_e32 v3, v3, v4
	v_mov_b32_e32 v4, v199
	s_nop 0
	v_lshlrev_b32_e32 v4, 2, v4
	v_bitop3_b32 v4, v4, s0, v193 bitop3:0x6c
	v_mov_b32_e32 v4, v3
	s_nop 1
	v_permlane32_swap_b32_e32 v4, v3
	s_and_saveexec_b64 s[0:1], vcc
	s_cbranch_execz .LBB0_426
	s_waitcnt lgkmcnt(0)
	v_add_f32_e32 v3, v3, v4
	ds_write_b32 v2, v3 offset:256

; DI float shx(float v, int mask) { return __int_as_float(__builtin_amdgcn_ds_bpermute((lane_now() ^ mask) << 2, __float_as_int(v))); }
; DI void st_bf16x4(bf16_t* p, f32x4 v) { u32x2 o; o.x = pk2e(v[0], v[1]); o.y = pk2e(v[2], v[3]); *(u32x2*)p = o; }
;     ...
;         for (int ai = 0; ai < 2; ++ai)
; #pragma unroll
;           for (int m = 0; m < 4; ++m) {
;             float v = rowss[ai][m];
;             v += shx(v, 16); v += shx(v, 32);
;             if (fq_e == 0) red[(ai * HALF + wr * 64 + m * 16 + fr_e) * 4 + wc] = v;
;           }
;   DI float operator()(int row, int colbase, int fq, f32x4 v0, f32x4 v1) const {
;     ...
;     const f32x4 a = *(const f32x4*)(src + o) + v0, b = *(const f32x4*)(src + o + 16) + v1;
;     *(f32x4*)(dst + o) = a; *(f32x4*)(dst + o + 16) = b;
;     if (xb) { st_bf16x4(xb + o, a); st_bf16x4(xb + o + 16, b); }
;     return ((a[0] * a[0] + a[1] * a[1]) + (a[2] * a[2] + a[3] * a[3])) + ((b[0] * b[0] + b[1] * b[1]) + (b[2] * b[2] + b[3] * b[3]));
.LBB0_428:
	s_or_b64 exec, exec, s[0:1]
	v_mul_f32_e32 v3, v91, v91
	s_waitcnt lgkmcnt(0)
	v_mul_f32_e32 v4, v93, v93
	v_fmac_f32_e32 v3, v90, v90
	v_fmac_f32_e32 v4, v92, v92
	v_add_f32_e32 v3, v3, v4
	v_mul_f32_e32 v4, v95, v95
	v_mul_f32_e32 v5, v97, v97
	v_fmac_f32_e32 v4, v94, v94
	v_fmac_f32_e32 v5, v96, v96
	v_add_f32_e32 v4, v4, v5
	v_add_f32_e32 v3, v3, v4
	v_mul_f32_e32 v4, v107, v107
	v_mul_f32_e32 v5, v109, v109
	v_fmac_f32_e32 v4, v106, v106
	v_fmac_f32_e32 v5, v108, v108
	v_add_f32_e32 v4, v4, v5
	v_mul_f32_e32 v5, v111, v111
	v_mul_f32_e32 v6, v113, v113
	v_fmac_f32_e32 v5, v110, v110
	v_fmac_f32_e32 v6, v112, v112
	v_add_f32_e32 v5, v5, v6
	v_add_f32_e32 v4, v4, v5
	v_add_f32_e32 v3, v3, v4
	v_mov_b32_e32 v4, v199
	s_movk_i32 s0, 0x80
	v_lshlrev_b32_e32 v4, 2, v4
	v_bitop3_b32 v4, v4, 64, v193 bitop3:0x6c
	v_mov_b32_e32 v4, v3
	s_nop 1
	v_permlane16_swap_b32_e32 v4, v3
	s_waitcnt lgkmcnt(0)
	v_add_f32_e32 v3, v3, v4
	v_mov_b32_e32 v4, v199
	s_nop 0
	v_lshlrev_b32_e32 v4, 2, v4
	v_bitop3_b32 v4, v4, s0, v193 bitop3:0x6c
	v_mov_b32_e32 v4, v3
	s_nop 1
	v_permlane32_swap_b32_e32 v4, v3
	s_and_saveexec_b64 s[0:1], vcc
	s_cbranch_execz .LBB0_430
	s_waitcnt lgkmcnt(0)
	v_add_f32_e32 v3, v3, v4
	ds_write_b32 v2, v3 offset:768

; DI float shx(float v, int mask) { return __int_as_float(__builtin_amdgcn_ds_bpermute((lane_now() ^ mask) << 2, __float_as_int(v))); }
; DI void st_bf16x4(bf16_t* p, f32x4 v) { u32x2 o; o.x = pk2e(v[0], v[1]); o.y = pk2e(v[2], v[3]); *(u32x2*)p = o; }
;     ...
;         for (int ai = 0; ai < 2; ++ai)
; #pragma unroll
;           for (int m = 0; m < 4; ++m) {
;             float v = rowss[ai][m];
;             v += shx(v, 16); v += shx(v, 32);
;             if (fq_e == 0) red[(ai * HALF + wr * 64 + m * 16 + fr_e) * 4 + wc] = v;
;           }
;   DI float operator()(int row, int colbase, int fq, f32x4 v0, f32x4 v1) const {
;     ...
;     const f32x4 a = *(const f32x4*)(src + o) + v0, b = *(const f32x4*)(src + o + 16) + v1;
;     *(f32x4*)(dst + o) = a; *(f32x4*)(dst + o + 16) = b;
;     if (xb) { st_bf16x4(xb + o, a); st_bf16x4(xb + o + 16, b); }
;     return ((a[0] * a[0] + a[1] * a[1]) + (a[2] * a[2] + a[3] * a[3])) + ((b[0] * b[0] + b[1] * b[1]) + (b[2] * b[2] + b[3] * b[3]));
.LBB0_432:
	s_or_b64 exec, exec, s[0:1]
	v_mul_f32_e32 v3, v103, v103
	s_waitcnt lgkmcnt(0)
	v_mul_f32_e32 v4, v105, v105
	v_fmac_f32_e32 v3, v102, v102
	v_fmac_f32_e32 v4, v104, v104
	v_add_f32_e32 v3, v3, v4
	v_mul_f32_e32 v4, v99, v99
	v_mul_f32_e32 v5, v101, v101
	v_fmac_f32_e32 v4, v98, v98
	v_fmac_f32_e32 v5, v100, v100
	v_add_f32_e32 v4, v4, v5
	v_add_f32_e32 v3, v3, v4
	v_mul_f32_e32 v4, v87, v87
	v_mul_f32_e32 v5, v89, v89
	v_fmac_f32_e32 v4, v86, v86
	v_fmac_f32_e32 v5, v88, v88
	v_add_f32_e32 v4, v4, v5
	v_mul_f32_e32 v5, v83, v83
	v_mul_f32_e32 v6, v85, v85
	v_fmac_f32_e32 v5, v82, v82
	v_fmac_f32_e32 v6, v84, v84
	v_add_f32_e32 v5, v5, v6
	v_add_f32_e32 v4, v4, v5
	v_add_f32_e32 v3, v3, v4
	v_mov_b32_e32 v4, v199
	s_movk_i32 s0, 0x80
	v_lshlrev_b32_e32 v4, 2, v4
	v_bitop3_b32 v4, v4, 64, v193 bitop3:0x6c
	v_mov_b32_e32 v4, v3
	s_nop 1
	v_permlane16_swap_b32_e32 v4, v3
	s_waitcnt lgkmcnt(0)
	v_add_f32_e32 v3, v3, v4
	v_mov_b32_e32 v4, v199
	s_nop 0
	v_lshlrev_b32_e32 v4, 2, v4
	v_bitop3_b32 v4, v4, s0, v193 bitop3:0x6c
	v_mov_b32_e32 v4, v3
	s_nop 1
	v_permlane32_swap_b32_e32 v4, v3
	s_and_saveexec_b64 s[0:1], vcc
	s_cbranch_execz .LBB0_434
	s_waitcnt lgkmcnt(0)
	v_add_f32_e32 v3, v3, v4
	ds_write_b32 v2, v3 offset:2304
.LBB0_434:
	s_or_b64 exec, exec, s[0:1]
	v_mul_f32_e32 v3, v71, v71
	s_waitcnt lgkmcnt(0)
	v_mul_f32_e32 v4, v73, v73
	v_fmac_f32_e32 v3, v70, v70
	v_fmac_f32_e32 v4, v72, v72
	v_add_f32_e32 v3, v3, v4
	v_mul_f32_e32 v4, v67, v67
	v_mul_f32_e32 v5, v69, v69
	v_fmac_f32_e32 v4, v66, v66
	v_fmac_f32_e32 v5, v68, v68
	v_add_f32_e32 v4, v4, v5
	v_add_f32_e32 v3, v3, v4
	v_mul_f32_e32 v4, v55, v55
	v_mul_f32_e32 v5, v57, v57
	v_fmac_f32_e32 v4, v54, v54
	v_fmac_f32_e32 v5, v56, v56
	v_add_f32_e32 v4, v4, v5
	v_mul_f32_e32 v5, v43, v43
	v_mul_f32_e32 v6, v45, v45
	v_fmac_f32_e32 v5, v42, v42
	v_fmac_f32_e32 v6, v44, v44
	v_add_f32_e32 v5, v5, v6
	v_add_f32_e32 v4, v4, v5
	v_add_f32_e32 v3, v3, v4
	v_mov_b32_e32 v4, v199
	s_movk_i32 s0, 0x80
	v_lshlrev_b32_e32 v4, 2, v4
	v_bitop3_b32 v4, v4, 64, v193 bitop3:0x6c
	v_mov_b32_e32 v4, v3
	s_nop 1
	v_permlane16_swap_b32_e32 v4, v3
	s_waitcnt lgkmcnt(0)
	v_add_f32_e32 v3, v3, v4
	v_mov_b32_e32 v4, v199
	s_nop 0
	v_lshlrev_b32_e32 v4, 2, v4
	v_bitop3_b32 v4, v4, s0, v193 bitop3:0x6c
	v_mov_b32_e32 v4, v3
	s_nop 1
	v_permlane32_swap_b32_e32 v4, v3
	s_and_saveexec_b64 s[0:1], vcc
	s_cbranch_execz .LBB0_436
	s_waitcnt lgkmcnt(0)
	v_add_f32_e32 v3, v3, v4
	ds_write_b32 v2, v3 offset:2560
